# odd attention: both score blocks issued back to back (K fragments streamed through dead P/V registers, accumulators interleaved, no hazard nops), s=1 MFMAs overlap the s=0 softmax
# speedup vs baseline: 1.0697x; 1.0112x over previous
.LBB0_430:
	ds_read_b128 v[198:201], v153
	ds_read_b128 v[202:205], v153 offset:4608
	ds_read_b128 v[206:209], v153 offset:9216
	ds_read_b128 v[210:213], v153 offset:13824
	ds_read_b128 v[216:219], v153 offset:64
	ds_read_b128 v[220:223], v153 offset:4672
	ds_read_b128 v[224:227], v153 offset:9280
	ds_read_b128 v[230:233], v153 offset:13888
	s_waitcnt lgkmcnt(7)
	v_mfma_f32_16x16x32_bf16 v[174:177], v[198:201], v[0:3], 0
	ds_read_b128 v[198:201], v153 offset:128
	s_waitcnt lgkmcnt(7)
	v_mfma_f32_16x16x32_bf16 v[160:163], v[202:205], v[0:3], 0
	ds_read_b128 v[202:205], v153 offset:4736
	s_waitcnt lgkmcnt(7)
	v_mfma_f32_16x16x32_bf16 v[166:169], v[206:209], v[0:3], 0
	ds_read_b128 v[206:209], v153 offset:9344
	s_waitcnt lgkmcnt(7)
	v_mfma_f32_16x16x32_bf16 v[170:173], v[210:213], v[0:3], 0
	ds_read_b128 v[210:213], v153 offset:13952
	s_waitcnt lgkmcnt(7)
	v_mfma_f32_16x16x32_bf16 v[174:177], v[216:219], v[4:7], v[174:177]
	ds_read_b128 v[216:219], v153 offset:192
	s_waitcnt lgkmcnt(7)
	v_mfma_f32_16x16x32_bf16 v[160:163], v[220:223], v[4:7], v[160:163]
	ds_read_b128 v[220:223], v153 offset:4800
	s_waitcnt lgkmcnt(7)
	v_mfma_f32_16x16x32_bf16 v[166:169], v[224:227], v[4:7], v[166:169]
	ds_read_b128 v[224:227], v153 offset:9408
	s_waitcnt lgkmcnt(7)
	v_mfma_f32_16x16x32_bf16 v[170:173], v[230:233], v[4:7], v[170:173]
	ds_read_b128 v[230:233], v153 offset:14016
	s_waitcnt lgkmcnt(7)
	v_mfma_f32_16x16x32_bf16 v[112:115], v[198:201], v[8:11], 0
	s_waitcnt lgkmcnt(6)
	v_mfma_f32_16x16x32_bf16 v[116:119], v[202:205], v[8:11], 0
	s_waitcnt lgkmcnt(5)
	v_mfma_f32_16x16x32_bf16 v[186:189], v[206:209], v[8:11], 0
	s_waitcnt lgkmcnt(4)
	v_mfma_f32_16x16x32_bf16 v[182:185], v[210:213], v[8:11], 0
	s_waitcnt lgkmcnt(3)
	v_mfma_f32_16x16x32_bf16 v[112:115], v[216:219], v[12:15], v[112:115]
	s_waitcnt lgkmcnt(2)
	v_mfma_f32_16x16x32_bf16 v[116:119], v[220:223], v[12:15], v[116:119]
	s_waitcnt lgkmcnt(1)
	v_mfma_f32_16x16x32_bf16 v[186:189], v[224:227], v[12:15], v[186:189]
	s_waitcnt lgkmcnt(0)
	v_mfma_f32_16x16x32_bf16 v[182:185], v[230:233], v[12:15], v[182:185]
	v_max3_f32 v194, v174, s30, v175
	v_max3_f32 v194, v194, v176, v177
	v_max3_f32 v194, v194, v160, v161
	v_max3_f32 v194, v194, v162, v163
	v_max3_f32 v194, v194, v166, v167
	v_max3_f32 v194, v194, v168, v169
	v_max3_f32 v194, v194, v170, v171
	v_max3_f32 v194, v194, v172, v173
	v_mov_b32_e32 v195, v194
	s_nop 1
	v_permlane16_swap_b32_e32 v194, v195
	v_max_f32_e32 v194, v194, v195
	v_mov_b32_e32 v195, v194
	s_nop 1
	v_permlane32_swap_b32_e32 v194, v195
	v_max_f32_e32 v194, v194, v195
	v_mul_f32_e32 v194, 0x3e38aa3b, v194
	v_max_f32_e32 v194, v155, v194
	v_pk_fma_f32 v[174:175], v[174:175], s[32:33], v[194:195] op_sel_hi:[1,0,0] neg_lo:[0,0,1] neg_hi:[0,0,1]
	v_pk_fma_f32 v[176:177], v[176:177], s[32:33], v[194:195] op_sel_hi:[1,0,0] neg_lo:[0,0,1] neg_hi:[0,0,1]
	v_pk_fma_f32 v[160:161], v[160:161], s[32:33], v[194:195] op_sel_hi:[1,0,0] neg_lo:[0,0,1] neg_hi:[0,0,1]
	v_pk_fma_f32 v[162:163], v[162:163], s[32:33], v[194:195] op_sel_hi:[1,0,0] neg_lo:[0,0,1] neg_hi:[0,0,1]
	v_pk_fma_f32 v[166:167], v[166:167], s[32:33], v[194:195] op_sel_hi:[1,0,0] neg_lo:[0,0,1] neg_hi:[0,0,1]
	v_pk_fma_f32 v[168:169], v[168:169], s[32:33], v[194:195] op_sel_hi:[1,0,0] neg_lo:[0,0,1] neg_hi:[0,0,1]
	v_pk_fma_f32 v[170:171], v[170:171], s[32:33], v[194:195] op_sel_hi:[1,0,0] neg_lo:[0,0,1] neg_hi:[0,0,1]
	v_pk_fma_f32 v[172:173], v[172:173], s[32:33], v[194:195] op_sel_hi:[1,0,0] neg_lo:[0,0,1] neg_hi:[0,0,1]
	v_cmp_gt_f32_e32 vcc, v194, v155
	s_cbranch_vccz .LBB0_432
	v_sub_f32_e32 v155, v155, v194
	v_exp_f32_e32 v215, v155
	v_mov_b32_e32 v155, v194
	v_mul_f32_e32 v131, v131, v215
	v_pk_mul_f32 v[98:99], v[98:99], v[214:215] op_sel:[0,1] op_sel_hi:[1,1]
	v_pk_mul_f32 v[96:97], v[96:97], v[214:215] op_sel:[0,1] op_sel_hi:[1,1]
	v_pk_mul_f32 v[102:103], v[102:103], v[214:215] op_sel:[0,1] op_sel_hi:[1,1]
	v_pk_mul_f32 v[100:101], v[100:101], v[214:215] op_sel:[0,1] op_sel_hi:[1,1]
	v_pk_mul_f32 v[70:71], v[70:71], v[214:215] op_sel:[0,1] op_sel_hi:[1,1]
	v_pk_mul_f32 v[68:69], v[68:69], v[214:215] op_sel:[0,1] op_sel_hi:[1,1]
	v_pk_mul_f32 v[54:55], v[54:55], v[214:215] op_sel:[0,1] op_sel_hi:[1,1]
	v_pk_mul_f32 v[52:53], v[52:53], v[214:215] op_sel:[0,1] op_sel_hi:[1,1]
	v_pk_mul_f32 v[82:83], v[82:83], v[214:215] op_sel:[0,1] op_sel_hi:[1,1]
	v_pk_mul_f32 v[80:81], v[80:81], v[214:215] op_sel:[0,1] op_sel_hi:[1,1]
	v_pk_mul_f32 v[86:87], v[86:87], v[214:215] op_sel:[0,1] op_sel_hi:[1,1]
	v_pk_mul_f32 v[84:85], v[84:85], v[214:215] op_sel:[0,1] op_sel_hi:[1,1]
	v_pk_mul_f32 v[78:79], v[78:79], v[214:215] op_sel:[0,1] op_sel_hi:[1,1]
	v_pk_mul_f32 v[76:77], v[76:77], v[214:215] op_sel:[0,1] op_sel_hi:[1,1]
	v_pk_mul_f32 v[110:111], v[110:111], v[214:215] op_sel:[0,1] op_sel_hi:[1,1]
	v_pk_mul_f32 v[108:109], v[108:109], v[214:215] op_sel:[0,1] op_sel_hi:[1,1]
.LBB0_432:
	v_exp_f32_e32 v174, v174
	v_exp_f32_e32 v175, v175
	v_exp_f32_e32 v176, v176
	v_exp_f32_e32 v177, v177
	v_exp_f32_e32 v160, v160
	v_exp_f32_e32 v161, v161
	v_exp_f32_e32 v162, v162
	v_exp_f32_e32 v163, v163
	v_exp_f32_e32 v166, v166
	v_exp_f32_e32 v167, v167
	v_exp_f32_e32 v168, v168
	v_exp_f32_e32 v169, v169
	v_exp_f32_e32 v170, v170
	v_exp_f32_e32 v171, v171
	v_exp_f32_e32 v172, v172
	v_exp_f32_e32 v173, v173
	s_nop 0
	v_cvt_pk_bf16_f32 v216, v174, v175
	v_cvt_pk_bf16_f32 v218, v160, v161
	v_cvt_pk_bf16_f32 v220, v166, v167
	v_cvt_pk_bf16_f32 v222, v170, v171
	v_pk_add_f32 v[174:175], v[174:175], v[176:177]
	v_pk_add_f32 v[160:161], v[160:161], v[162:163]
	v_pk_add_f32 v[166:167], v[166:167], v[168:169]
	v_pk_add_f32 v[170:171], v[170:171], v[172:173]
	v_pk_add_f32 v[174:175], v[174:175], v[160:161]
	v_pk_add_f32 v[170:171], v[170:171], v[166:167]
	v_cvt_pk_bf16_f32 v217, v176, v177
	v_pk_add_f32 v[170:171], v[170:171], v[174:175]
	v_cvt_pk_bf16_f32 v219, v162, v163
	v_add_f32_e32 v170, v170, v171
	v_cvt_pk_bf16_f32 v221, v168, v169
	v_add_f32_e32 v131, v170, v131
	v_cvt_pk_bf16_f32 v223, v172, v173
	v_max3_f32 v194, v112, s30, v113
	v_max3_f32 v194, v194, v114, v115
	v_max3_f32 v194, v194, v116, v117
	v_max3_f32 v194, v194, v118, v119
	v_max3_f32 v194, v194, v186, v187
	v_max3_f32 v194, v194, v188, v189
	v_max3_f32 v194, v194, v182, v183
	v_max3_f32 v194, v194, v184, v185
	v_mov_b32_e32 v195, v194
	s_nop 1
	v_permlane16_swap_b32_e32 v194, v195
	v_max_f32_e32 v194, v194, v195
	v_mov_b32_e32 v195, v194
	s_nop 1
	v_permlane32_swap_b32_e32 v194, v195
	v_max_f32_e32 v194, v194, v195
	v_mul_f32_e32 v194, 0x3e38aa3b, v194
	v_max_f32_e32 v194, v156, v194
	v_pk_fma_f32 v[112:113], v[112:113], s[32:33], v[194:195] op_sel_hi:[1,0,0] neg_lo:[0,0,1] neg_hi:[0,0,1]
	v_pk_fma_f32 v[114:115], v[114:115], s[32:33], v[194:195] op_sel_hi:[1,0,0] neg_lo:[0,0,1] neg_hi:[0,0,1]
	v_pk_fma_f32 v[116:117], v[116:117], s[32:33], v[194:195] op_sel_hi:[1,0,0] neg_lo:[0,0,1] neg_hi:[0,0,1]
	v_pk_fma_f32 v[118:119], v[118:119], s[32:33], v[194:195] op_sel_hi:[1,0,0] neg_lo:[0,0,1] neg_hi:[0,0,1]
	v_pk_fma_f32 v[186:187], v[186:187], s[32:33], v[194:195] op_sel_hi:[1,0,0] neg_lo:[0,0,1] neg_hi:[0,0,1]
	v_pk_fma_f32 v[188:189], v[188:189], s[32:33], v[194:195] op_sel_hi:[1,0,0] neg_lo:[0,0,1] neg_hi:[0,0,1]
	v_pk_fma_f32 v[182:183], v[182:183], s[32:33], v[194:195] op_sel_hi:[1,0,0] neg_lo:[0,0,1] neg_hi:[0,0,1]
	v_pk_fma_f32 v[184:185], v[184:185], s[32:33], v[194:195] op_sel_hi:[1,0,0] neg_lo:[0,0,1] neg_hi:[0,0,1]
	v_cmp_gt_f32_e32 vcc, v194, v156
	s_cbranch_vccz .LBB0_434
	v_sub_f32_e32 v156, v156, v194
	v_exp_f32_e32 v156, v156
	s_nop 0
	v_mul_f32_e32 v121, v121, v156
	v_pk_mul_f32 v[94:95], v[94:95], v[156:157] op_sel_hi:[1,0]
	v_pk_mul_f32 v[92:93], v[92:93], v[156:157] op_sel_hi:[1,0]
	v_pk_mul_f32 v[90:91], v[90:91], v[156:157] op_sel_hi:[1,0]
	v_pk_mul_f32 v[88:89], v[88:89], v[156:157] op_sel_hi:[1,0]
	v_pk_mul_f32 v[58:59], v[58:59], v[156:157] op_sel_hi:[1,0]
	v_pk_mul_f32 v[56:57], v[56:57], v[156:157] op_sel_hi:[1,0]
	v_pk_mul_f32 v[50:51], v[50:51], v[156:157] op_sel_hi:[1,0]
	v_pk_mul_f32 v[48:49], v[48:49], v[156:157] op_sel_hi:[1,0]
	v_pk_mul_f32 v[66:67], v[66:67], v[156:157] op_sel_hi:[1,0]
	v_pk_mul_f32 v[64:65], v[64:65], v[156:157] op_sel_hi:[1,0]
	v_pk_mul_f32 v[74:75], v[74:75], v[156:157] op_sel_hi:[1,0]
	v_pk_mul_f32 v[72:73], v[72:73], v[156:157] op_sel_hi:[1,0]
	v_pk_mul_f32 v[62:63], v[62:63], v[156:157] op_sel_hi:[1,0]
	v_pk_mul_f32 v[60:61], v[60:61], v[156:157] op_sel_hi:[1,0]
	v_pk_mul_f32 v[106:107], v[106:107], v[156:157] op_sel_hi:[1,0]
	v_pk_mul_f32 v[104:105], v[104:105], v[156:157] op_sel_hi:[1,0]
	v_mov_b32_e32 v156, v194
